# prologue/final norm: global wave index = wave*G + block (was block*8 + wave) so the weight-transpose items spread over all CUs
# speedup vs baseline: 1.0112x; 1.0112x over previous
; #define LAS __attribute__((address_space(3)))
; #define PH_BEGIN if (ph >= lo && ph < hi_) {
; __global__ void __launch_bounds__(512, 2) fwd_kernel(Args a) {
;     ...
;     const int G = (int)gridDim.x, gw = (int)blockIdx.x * 8 + wave, NGW = G * 8;
;     ...
;     PH_BEGIN
;     {
;         LAS float* scr = (LAS float*)(lds + wave * 8448);
;         for (int l = 0; l < 4; ++l) {
;             transpose_matrix(a.f_wg + (size_t)l * DM * FF, DM, FF, Wgu + (size_t)l * NGU * DM, 1, scr, gw, NGW, lane, a.norm_ffn_g + l * DM);
;             transpose_matrix(a.f_wu + (size_t)l * DM * FF, DM, FF, Wgu + (size_t)l * NGU * DM, 2, scr, gw, NGW, lane, a.norm_ffn_g + l * DM);
;             transpose_matrix(a.f_wd + (size_t)l * FF * DM, FF, DM, Wd + (size_t)l * DM * FF, 0, scr, gw, NGW, lane);
;         }
;         transpose_matrix(a.w_qkv, DM, NQKV, Wqkv, 0, scr, gw, NGW, lane, a.norm_mix_g + 1 * DM);
;         transpose_matrix(a.w_o, DM, DM, Wo, 0, scr, gw, NGW, lane);
.LBB0_15:
	s_load_dwordx16 s[36:51], s[0:1], 0x40
	v_writelane_b32 v247, s14, 24
	s_add_u32 s82, s76, 0x1d400000
	s_addc_u32 s83, s77, 0
	v_writelane_b32 v247, s15, 25
	s_waitcnt lgkmcnt(0)
	v_writelane_b32 v247, s36, 26
	s_load_dwordx16 s[4:19], s[0:1], 0x80
	s_add_u32 s86, s76, 0x1d604000
	v_writelane_b32 v247, s37, 27
	v_writelane_b32 v247, s38, 28
	v_writelane_b32 v247, s39, 29
	v_writelane_b32 v247, s40, 30
	v_writelane_b32 v247, s41, 31
	v_writelane_b32 v247, s42, 32
	v_writelane_b32 v247, s43, 33
	v_writelane_b32 v247, s44, 34
	v_writelane_b32 v247, s45, 35
	v_writelane_b32 v247, s46, 36
	v_writelane_b32 v247, s47, 37
	v_writelane_b32 v247, s48, 38
	v_writelane_b32 v247, s49, 39
	v_writelane_b32 v247, s50, 40
	v_writelane_b32 v247, s51, 41
	s_waitcnt lgkmcnt(0)
	v_writelane_b32 v247, s4, 42
	s_addc_u32 s87, s77, 0
	s_add_u32 s0, s76, 0x1cd00000
	v_writelane_b32 v247, s5, 43
	v_writelane_b32 v247, s6, 44
	v_writelane_b32 v247, s7, 45
	v_writelane_b32 v247, s8, 46
	v_writelane_b32 v247, s9, 47
	v_writelane_b32 v247, s10, 48
	v_writelane_b32 v247, s11, 49
	v_writelane_b32 v247, s12, 50
	v_writelane_b32 v247, s13, 51
	v_writelane_b32 v247, s14, 52
	v_writelane_b32 v247, s15, 53
	v_writelane_b32 v247, s16, 54
	s_addc_u32 s1, s77, 0
	v_writelane_b32 v247, s17, 55
	s_add_u32 s96, s76, 0x1d100000
	v_writelane_b32 v247, s18, 56
	s_addc_u32 s97, s77, 0
	v_writelane_b32 v247, s19, 57
	s_add_u32 s12, s76, 0x1d300000
	s_addc_u32 s13, s77, 0
	s_lshl_b32 s33, s88, 3
	s_add_u32 s80, s76, 0x8100000
	s_addc_u32 s81, s77, 0
	s_add_u32 s84, s76, 0x18300000
	v_writelane_b32 v247, s0, 58
	s_addc_u32 s85, s77, 0
	v_and_b32_e32 v164, 63, v163
	v_writelane_b32 v247, s1, 59
	s_add_u32 s0, s76, 0x1af00000
	s_addc_u32 s1, s77, 0
	s_add_u32 s94, s76, 0x1c500000
	v_writelane_b32 v247, s0, 60
	s_addc_u32 s95, s77, 0
	v_lshrrev_b32_e32 v165, 6, v163
	v_writelane_b32 v247, s1, 61
	s_add_u32 s0, s76, 0x1cb00000
	s_addc_u32 s1, s77, 0
	s_cmp_lt_i32 s78, 1
	s_cselect_b64 s[8:9], -1, 0
	s_cmp_gt_i32 s79, 0
	s_cselect_b64 s[4:5], -1, 0
	v_writelane_b32 v247, s0, 62
	s_and_b64 s[4:5], s[8:9], s[4:5]
	v_mul_u32_u24_e32 v162, s88, v165
	v_add_u32_e32 v162, s2, v162
	v_writelane_b32 v247, s1, 63
	s_mov_b32 s1, 0
	s_andn2_b64 vcc, exec, s[4:5]
	v_lshrrev_b32_e32 v169, 5, v164
	v_and_b32_e32 v168, 31, v163
	s_cbranch_vccnz .LBB0_61
	s_movk_i32 s0, 0x2100
	v_mad_u32_u24 v2, v165, s0, 0
	v_lshlrev_b32_e32 v10, 2, v168
	v_mul_u32_u24_e32 v3, 0x84, v169
	v_readlane_b32 s16, v247, 8
	v_add3_u32 v13, v2, v10, v3
	v_lshlrev_b32_e32 v3, 3, v163
	v_readlane_b32 s36, v247, 0
	v_readlane_b32 s22, v247, 14
	v_readlane_b32 s23, v247, 15
	v_lshrrev_b32_e32 v60, 3, v164
	v_and_b32_e32 v4, 56, v3
	v_mov_b32_e32 v11, 0
	v_readlane_b32 s37, v247, 1
	v_readlane_b32 s38, v247, 2
	v_readlane_b32 s39, v247, 3
	v_readlane_b32 s40, v247, 4
	v_readlane_b32 s41, v247, 5
	s_cmp_lg_u64 s[22:23], 0
	v_mul_u32_u24_e32 v3, 0x84, v4
	v_lshlrev_b32_e32 v5, 2, v60
	v_readlane_b32 s6, v247, 60
	s_movk_i32 s0, 0x580
	v_readlane_b32 s42, v247, 6
	v_lshl_add_u64 v[0:1], s[36:37], 0, v[10:11]
	v_add3_u32 v61, v2, v3, v5
	v_lshl_add_u64 v[2:3], s[38:39], 0, v[10:11]
	v_lshl_add_u64 v[6:7], s[40:41], 0, v[10:11]
	v_lshlrev_b32_e32 v10, 1, v4
	v_readlane_b32 s7, v247, 61
	s_cselect_b64 s[10:11], -1, 0
	v_cmp_gt_i32_e64 s[4:5], s0, v162
	v_or_b32_e32 v62, 8, v60
	v_or_b32_e32 v63, 16, v60
	v_or_b32_e32 v64, 24, v60
	v_lshl_add_u64 v[8:9], s[6:7], 0, v[10:11]
	v_lshl_add_u64 v[10:11], s[84:85], 0, v[10:11]
	v_mul_u32_u24_e32 v12, 0xb00, v60
	v_lshlrev_b32_e32 v5, 5, v162
	s_mov_b32 s3, 0x2e8ba2e9
	s_movk_i32 s38, 0xf500
	s_movk_i32 s39, 0x2c00
	v_cndmask_b32_e64 v65, 0, 1, s[10:11]
	s_movk_i32 s40, 0xffa8
	s_movk_i32 s41, 0x57f
	v_mov_b32_e32 v66, 0xb00000
	v_mov_b32_e32 v67, 13
	v_mov_b32_e32 v68, 2
	s_mov_b32 s42, 0
	v_readlane_b32 s43, v247, 7
	v_readlane_b32 s17, v247, 9
	v_readlane_b32 s18, v247, 10
	v_readlane_b32 s19, v247, 11
	v_readlane_b32 s20, v247, 12
	v_readlane_b32 s21, v247, 13
	v_readlane_b32 s24, v247, 16
	v_readlane_b32 s25, v247, 17
	v_readlane_b32 s26, v247, 18
	v_readlane_b32 s27, v247, 19
	v_readlane_b32 s28, v247, 20
	v_readlane_b32 s29, v247, 21
	v_readlane_b32 s30, v247, 22
	v_readlane_b32 s31, v247, 23
	s_branch .LBB0_18
